# phase 15: selected-to-window hand-off resets the running state in place and the first window tile (also when cut by the lower window edge) goes through the masked fast path
# baseline (speedup 1.0000x reference)
; __device__ __forceinline__ uint2 pack4(f32x4 v) { return make_uint2(pack2(v[0], v[1]), pack2(v[2], v[3])); }
; __device__ __forceinline__ void nsa_finish(NsaState& st, f32x4 (&out)[2][4], const float (&gate)[2]) {
; #pragma unroll
;   for (int hh = 0; hh < 2; ++hh) {
;     const float l = st.accL[hh][0];
;     const float sc = (l > 0.f) ? gate[hh] / l : 0.f;
; #pragma unroll
;     for (int dm = 0; dm < 4; ++dm) out[hh][dm] += st.acc[hh][dm] * sc;
;   }
; }
; __device__ __forceinline__ void phase_nsa_sw(const Params& p, u16* sm) {
;     ...
;       if (i == nsel) {
;         f32x4 tmp[2][4];
; #pragma unroll
;         for (int hh = 0; hh < 2; ++hh)
; #pragma unroll
;           for (int dm = 0; dm < 4; ++dm) tmp[hh][dm] = (f32x4){0.f, 0.f, 0.f, 0.f};
;         const float gg[2] = {gates[0][1], gates[1][1]};
;         nsa_finish(st, tmp, gg);
; #pragma unroll
;         for (int hh = 0; hh < 2; ++hh)
; #pragma unroll
;           for (int dm = 0; dm < 4; ++dm) selL[(hh * 4 + dm) * 64] = pack4(tmp[hh][dm]);
;         nsa_reset(st);
;       }
.Lfp15_park:
	v_div_scale_f32 v1, s[8:9], v48, v48, v208
	v_rcp_f32_e32 v2, v1
	v_div_scale_f32 v3, vcc, v208, v48, v208
	v_div_scale_f32 v44, s[8:9], v132, v132, v206
	v_fma_f32 v28, -v1, v2, 1.0
	v_fmac_f32_e32 v2, v28, v2
	v_mul_f32_e32 v28, v3, v2
	v_fma_f32 v29, -v1, v28, v3
	v_rcp_f32_e32 v45, v44
	v_fmac_f32_e32 v28, v29, v2
	v_fma_f32 v1, -v1, v28, v3
	v_div_fmas_f32 v1, v1, v2, v28
	v_div_fixup_f32 v1, v1, v48, v208
	v_cmp_lt_f32_e32 vcc, 0, v48
	v_fma_f32 v46, -v44, v45, 1.0
	v_fmac_f32_e32 v45, v46, v45
	v_cndmask_b32_e32 v28, 0, v1, vcc
	v_div_scale_f32 v46, vcc, v206, v132, v206
	v_mul_f32_e32 v47, v46, v45
	v_fma_f32 v48, -v44, v47, v46
	v_fmac_f32_e32 v47, v48, v45
	v_fma_f32 v44, -v44, v47, v46
	v_div_fmas_f32 v44, v44, v45, v47
	v_pk_fma_f32 v[30:31], v[54:55], v[28:29], 0 op_sel_hi:[1,0,0]
	v_pk_fma_f32 v[32:33], v[52:53], v[28:29], 0 op_sel_hi:[1,0,0]
	v_pk_fma_f32 v[34:35], v[58:59], v[28:29], 0 op_sel_hi:[1,0,0]
	v_pk_fma_f32 v[36:37], v[56:57], v[28:29], 0 op_sel_hi:[1,0,0]
	v_div_fixup_f32 v44, v44, v132, v206
	v_cmp_lt_f32_e32 vcc, 0, v132
	v_pk_fma_f32 v[38:39], v[62:63], v[28:29], 0 op_sel_hi:[1,0,0]
	v_pk_fma_f32 v[40:41], v[60:61], v[28:29], 0 op_sel_hi:[1,0,0]
	v_pk_fma_f32 v[42:43], v[66:67], v[28:29], 0 op_sel_hi:[1,0,0]
	v_pk_fma_f32 v[28:29], v[64:65], v[28:29], 0 op_sel_hi:[1,0,0]
	v_cndmask_b32_e32 v44, 0, v44, vcc
	v_cvt_pk_bf16_f32 v32, v32, v33
	v_cvt_pk_bf16_f32 v33, v30, v31
	v_cvt_pk_bf16_f32 v30, v36, v37
	v_cvt_pk_bf16_f32 v31, v34, v35
	v_pk_fma_f32 v[46:47], v[118:119], v[44:45], 0 op_sel_hi:[1,0,0]
	v_pk_fma_f32 v[48:49], v[116:117], v[44:45], 0 op_sel_hi:[1,0,0]
	v_pk_fma_f32 v[50:51], v[114:115], v[44:45], 0 op_sel_hi:[1,0,0]
	v_pk_fma_f32 v[52:53], v[112:113], v[44:45], 0 op_sel_hi:[1,0,0]
	ds_write2st64_b64 v179, v[32:33], v[30:31] offset0:73 offset1:74
	v_cvt_pk_bf16_f32 v30, v40, v41
	v_cvt_pk_bf16_f32 v31, v38, v39
	v_cvt_pk_bf16_f32 v28, v28, v29
	v_cvt_pk_bf16_f32 v29, v42, v43
	v_pk_fma_f32 v[54:55], v[110:111], v[44:45], 0 op_sel_hi:[1,0,0]
	v_pk_fma_f32 v[56:57], v[108:109], v[44:45], 0 op_sel_hi:[1,0,0]
	v_pk_fma_f32 v[58:59], v[106:107], v[44:45], 0 op_sel_hi:[1,0,0]
	v_pk_fma_f32 v[44:45], v[104:105], v[44:45], 0 op_sel_hi:[1,0,0]
	ds_write2st64_b64 v179, v[30:31], v[28:29] offset0:75 offset1:76
	v_cvt_pk_bf16_f32 v28, v48, v49
	v_cvt_pk_bf16_f32 v29, v46, v47
	v_cvt_pk_bf16_f32 v30, v52, v53
	v_cvt_pk_bf16_f32 v31, v50, v51
	v_mov_b32_e32 v2, v0
	v_mov_b32_e32 v3, v0
	ds_write2st64_b64 v179, v[28:29], v[30:31] offset0:77 offset1:78
	v_cvt_pk_bf16_f32 v28, v56, v57
	v_cvt_pk_bf16_f32 v29, v54, v55
	v_cvt_pk_bf16_f32 v30, v44, v45
	v_cvt_pk_bf16_f32 v31, v58, v59
	v_mov_b32_e32 v1, v0
	ds_write2st64_b64 v179, v[28:29], v[30:31] offset0:79 offset1:80
	v_mov_b64_e32 v[48:49], v[0:1]
	v_mov_b64_e32 v[50:51], v[0:1]
	v_mov_b64_e32 v[52:53], v[0:1]
	v_mov_b64_e32 v[54:55], v[0:1]
	v_mov_b64_e32 v[56:57], v[0:1]
	v_mov_b64_e32 v[58:59], v[0:1]
	v_mov_b64_e32 v[60:61], v[0:1]
	v_mov_b64_e32 v[62:63], v[0:1]
	v_mov_b64_e32 v[64:65], v[0:1]
	v_mov_b64_e32 v[66:67], v[0:1]
	v_mov_b64_e32 v[104:105], v[0:1]
	v_mov_b64_e32 v[106:107], v[0:1]
	v_mov_b64_e32 v[108:109], v[0:1]
	v_mov_b64_e32 v[110:111], v[0:1]
	v_mov_b64_e32 v[112:113], v[0:1]
	v_mov_b64_e32 v[114:115], v[0:1]
	v_mov_b64_e32 v[116:117], v[0:1]
	v_mov_b64_e32 v[118:119], v[0:1]
	v_mov_b64_e32 v[132:133], v[0:1]
	v_mov_b64_e32 v[134:135], v[0:1]
	v_mov_b32_e32 v234, 0xf149f2ca
	v_mov_b32_e32 v235, 0xf149f2ca
	s_branch .Lfp15_win

; __device__ __forceinline__ void phase_nsa_sw(const Params& p, u16* sm) {
;     ...
;       nsa_qk(s, cK, qf, fr, fq);
;       {
;         const bool is_sel = (v < 64);
;         const int kt = is_sel ? v : v - 64;
;         const bool lv = is_sel ? (bool)((mymask >> v) & 1ull) : true;
;         const bool masked = is_sel ? (v == (t0 >> 6)) : !((64 * kt + 63 <= t0) && (64 * kt >= t0 - 480));
;         if (masked) {
;           const int wnd = is_sel ? (1 << 30) : 512;
;           unsigned vmask = 0;
; #pragma unroll
;           for (int mt = 0; mt < 4; ++mt)
; #pragma unroll
;             for (int j = 0; j < 4; ++j) {
;               const int key = kt * 64 + 32 * (mt >> 1) + 8 * fq + 4 * (mt & 1) + j;
;               const int diff = myt - key;
;               vmask |= ((lv && diff >= 0 && diff < wnd) ? 1u : 0u) << (mt * 4 + j);
;             }
;           nsa_online_step<true>(st, s, vmask, true, cV, fr, fq);
;         } else {
;           nsa_online_step<false>(st, s, 0u, lv, cV, fr, fq);
.Lfp15_win:
	s_lshl_b32 s8, s14, 6
	s_add_i32 s8, s8, 0xfffff000
	s_or_b32 s9, s8, 63
	s_cmp_gt_i32 s9, s44
	s_cbranch_scc1 .Lfp15m_body
	s_cmp_lt_i32 s8, s82
	s_cbranch_scc0 .Lfp15_body
	s_branch .Lfp15m_body
